# P2: workgroups with a spare tile slot (jl>=20) start half a tile late to de-phase epilogue HBM bursts
# speedup vs baseline: 1.0036x; 1.0014x over previous
; DI void phase2(const Params& p, char* smem) {
;   const int xcd = blockIdx.x & 7, jl = blockIdx.x >> 3, nl = gridDim.x >> 3;
;   auto decode = [&](int L, int& tokTile, int& ft) {
;     if (L < 416) { const int tg = L / 104, rem = L % 104; ft = rem >> 3; tokTile = xcd * 32 + tg * 8 + (rem & 7); }
;     else { const int u = L - 416; tokTile = 256 + xcd * 4 + (u >> 1); ft = 1 + (u & 1); }
;   };
;   bool pre = false;
;   for (int L = jl; L < 416 + 8; L += nl) {
;     int tokTile, ft, tokTileN = 0, ftN = 0;
;     decode(L, tokTile, ft);
;     const bool lat = L < 416;
;     const int Ln = L + nl; const bool hasNext = Ln < 416 + 8;
;     if (hasNext) decode(Ln, tokTileN, ftN);
.LBB0_198:
	s_or_b64 exec, exec, s[4:5]
	s_and_b32 s4, s2, 7
	s_lshr_b32 s95, s3, 3
	s_lshr_b32 s96, s2, 3
	s_lshl_b32 s62, s4, 2
	s_lshl_b32 s55, s4, 5
	s_cmpk_gt_u32 s2, 0xd3f
	s_barrier
	v_writelane_b32 v252, s4, 3
	s_cbranch_scc1 .LBB0_302
	s_cmp_lt_u32 s96, 20
	s_cbranch_scc1 .Lp2_nostagger
	s_sleep 127
	s_sleep 127
	s_sleep 127
	s_sleep 127
	s_sleep 127
.Lp2_nostagger:
	s_load_dwordx2 s[14:15], s[0:1], 0x60
	s_load_dwordx8 s[16:23], s[0:1], 0xc0
	s_or_b32 s53, s62, 0x100
	s_load_dwordx2 s[24:25], s[0:1], 0xe0
	s_movk_i32 s52, 0x100
	s_waitcnt lgkmcnt(0)
	s_add_u32 s26, s14, 0x80
	s_addc_u32 s27, s15, 0
	s_add_u32 s28, s16, 0x80
	s_addc_u32 s29, s17, 0
	s_mov_b64 s[4:5], 0
	s_mov_b32 s31, 0
	s_movk_i32 s54, 0xc0
	s_movk_i32 s56, 0x80
	v_mov_b32_e32 v185, 0
	s_mov_b32 s57, 0x8000
	s_mov_b32 s58, 0x10000
	s_mov_b32 s59, 0xfffffe0
	s_movk_i32 s60, 0x210
	s_movk_i32 s61, 0x1000
	s_movk_i32 s63, 0xffc0
	s_movk_i32 s64, 0xdff
	s_mov_b32 s65, s96
	s_waitcnt vmcnt(0)
	s_branch .LBB0_201
